# strategy 5 (direct HBM->LDS loads): dwconv input tile streamed with global_load_lds when the chunk needs no causal zero rows; VGPR path kept for the first chunk of a sequence
# baseline (speedup 1.0000x reference)
.LBB0_720:
	s_lshl_b32 s9, s8, 5
	s_and_saveexec_b64 s[0:1], s[40:41]
	s_cbranch_execz .LBB0_725
	s_ashr_i32 s4, s9, 31
	s_lshr_b32 s4, s4, 21
	s_add_i32 s4, s9, s4
	s_and_b32 s4, s4, 0xfffff800
	s_sub_i32 s10, s4, s9
	s_add_i32 s10, s10, 29
	s_sub_i32 s11, s9, 30
	s_cmp_lt_i32 s10, 0
	s_cbranch_scc0 .Ldw_vgpr_path
	s_mov_b32 s100, s11
	s_ashr_i32 s101, s11, 31
	s_lshl_b64 s[100:101], s[100:101], 11
	s_add_u32 s100, s100, s62
	s_addc_u32 s101, s101, s63
	v_lshlrev_b32_e32 v0, 4, v188
	s_lshl_b32 s4, s97, 4
	s_mov_b32 m0, s4
	s_nop 0
	global_load_lds_dwordx4 v0, s[100:101]
	s_add_u32 s100, s100, 0x2000
	s_addc_u32 s101, s101, 0
	s_add_i32 m0, s4, 0x2000
	s_nop 0
	global_load_lds_dwordx4 v0, s[100:101]
	s_add_u32 s100, s100, 0x2000
	s_addc_u32 s101, s101, 0
	s_add_i32 m0, s4, 0x4000
	s_nop 0
	global_load_lds_dwordx4 v0, s[100:101]
	s_add_u32 s100, s100, 0x2000
	s_addc_u32 s101, s101, 0
	s_add_i32 m0, s4, 0x6000
	s_nop 0
	global_load_lds_dwordx4 v0, s[100:101]
	s_add_u32 s100, s100, 0x2000
	s_addc_u32 s101, s101, 0
	s_add_i32 m0, s4, 0x8000
	s_nop 0
	global_load_lds_dwordx4 v0, s[100:101]
	s_add_u32 s100, s100, 0x2000
	s_addc_u32 s101, s101, 0
	s_add_i32 m0, s4, 0xa000
	s_nop 0
	global_load_lds_dwordx4 v0, s[100:101]
	s_add_u32 s100, s100, 0x2000
	s_addc_u32 s101, s101, 0
	s_add_i32 m0, s4, 0xc000
	s_nop 0
	global_load_lds_dwordx4 v0, s[100:101]
	s_add_u32 s100, s100, 0x2000
	s_addc_u32 s101, s101, 0
	s_add_i32 m0, s4, 0xe000
	s_nop 0
	global_load_lds_dwordx4 v0, s[100:101]
	s_add_u32 s100, s100, 0x2000
	s_addc_u32 s101, s101, 0
	s_add_i32 m0, s4, 0x10000
	s_nop 0
	global_load_lds_dwordx4 v0, s[100:101]
	s_add_u32 s100, s100, 0x2000
	s_addc_u32 s101, s101, 0
	s_add_i32 m0, s4, 0x12000
	s_nop 0
	global_load_lds_dwordx4 v0, s[100:101]
	s_add_u32 s100, s100, 0x2000
	s_addc_u32 s101, s101, 0
	s_add_i32 m0, s4, 0x14000
	s_nop 0
	global_load_lds_dwordx4 v0, s[100:101]
	s_add_u32 s100, s100, 0x2000
	s_addc_u32 s101, s101, 0
	s_add_i32 m0, s4, 0x16000
	s_nop 0
	global_load_lds_dwordx4 v0, s[100:101]
	s_add_u32 s100, s100, 0x2000
	s_addc_u32 s101, s101, 0
	s_add_i32 m0, s4, 0x18000
	s_nop 0
	global_load_lds_dwordx4 v0, s[100:101]
	s_add_u32 s100, s100, 0x2000
	s_addc_u32 s101, s101, 0
	s_add_i32 m0, s4, 0x1a000
	s_nop 0
	global_load_lds_dwordx4 v0, s[100:101]
	s_add_u32 s100, s100, 0x2000
	s_addc_u32 s101, s101, 0
	s_add_i32 m0, s4, 0x1c000
	s_nop 0
	global_load_lds_dwordx4 v0, s[100:101]
	s_add_u32 s100, s100, 0x2000
	s_addc_u32 s101, s101, 0
	s_cmp_lt_u32 s97, 0x100
	s_cbranch_scc0 .LBB0_725
	s_add_i32 m0, s4, 0x1e000
	s_nop 0
	global_load_lds_dwordx4 v0, s[100:101]
	s_branch .LBB0_725
.Ldw_vgpr_path:
	v_lshrrev_b32_e32 v44, 7, v188
	v_and_b32_e32 v0, 0x7f, v188
	v_lshlrev_b32_e32 v0, 4, v0
	s_movk_i32 s4, 0x100
	v_cmp_gt_u32_e64 s[12:13], s4, v188
	s_mov_b64 s[4:5], exec
	v_add_u32_e32 v42, 0, v44
	v_mov_b32_e32 v8, 0
	v_mov_b32_e32 v9, 0
	v_mov_b32_e32 v10, 0
	v_mov_b32_e32 v11, 0
	v_cmp_lt_i32_e32 vcc, s10, v42
	s_and_saveexec_b64 s[6:7], vcc
	v_add_u32_e32 v40, s11, v42
	v_ashrrev_i32_e32 v41, 31, v40
	v_lshlrev_b64 v[40:41], 11, v[40:41]
	v_lshl_add_u64 v[40:41], s[62:63], 0, v[40:41]
	v_lshl_add_u64 v[40:41], v[40:41], 0, v[0:1]
	global_load_dwordx4 v[8:11], v[40:41], off
	s_mov_b64 exec, s[4:5]
	v_add_u32_e32 v42, 4, v44
	v_mov_b32_e32 v12, 0
	v_mov_b32_e32 v13, 0
	v_mov_b32_e32 v14, 0
	v_mov_b32_e32 v15, 0
	v_cmp_lt_i32_e32 vcc, s10, v42
	s_and_saveexec_b64 s[6:7], vcc
	v_add_u32_e32 v40, s11, v42
	v_ashrrev_i32_e32 v41, 31, v40
	v_lshlrev_b64 v[40:41], 11, v[40:41]
	v_lshl_add_u64 v[40:41], s[62:63], 0, v[40:41]
	v_lshl_add_u64 v[40:41], v[40:41], 0, v[0:1]
	global_load_dwordx4 v[12:15], v[40:41], off
	s_mov_b64 exec, s[4:5]
	v_add_u32_e32 v42, 8, v44
	v_mov_b32_e32 v16, 0
	v_mov_b32_e32 v17, 0
	v_mov_b32_e32 v18, 0
	v_mov_b32_e32 v19, 0
	v_cmp_lt_i32_e32 vcc, s10, v42
	s_and_saveexec_b64 s[6:7], vcc
	v_add_u32_e32 v40, s11, v42
	v_ashrrev_i32_e32 v41, 31, v40
	v_lshlrev_b64 v[40:41], 11, v[40:41]
	v_lshl_add_u64 v[40:41], s[62:63], 0, v[40:41]
	v_lshl_add_u64 v[40:41], v[40:41], 0, v[0:1]
	global_load_dwordx4 v[16:19], v[40:41], off
	s_mov_b64 exec, s[4:5]
	v_add_u32_e32 v42, 12, v44
	v_mov_b32_e32 v20, 0
	v_mov_b32_e32 v21, 0
	v_mov_b32_e32 v22, 0
	v_mov_b32_e32 v23, 0
	v_cmp_lt_i32_e32 vcc, s10, v42
	s_and_saveexec_b64 s[6:7], vcc
	v_add_u32_e32 v40, s11, v42
	v_ashrrev_i32_e32 v41, 31, v40
	v_lshlrev_b64 v[40:41], 11, v[40:41]
	v_lshl_add_u64 v[40:41], s[62:63], 0, v[40:41]
	v_lshl_add_u64 v[40:41], v[40:41], 0, v[0:1]
	global_load_dwordx4 v[20:23], v[40:41], off
	s_mov_b64 exec, s[4:5]
	v_add_u32_e32 v42, 16, v44
	v_mov_b32_e32 v24, 0
	v_mov_b32_e32 v25, 0
	v_mov_b32_e32 v26, 0
	v_mov_b32_e32 v27, 0
	v_cmp_lt_i32_e32 vcc, s10, v42
	s_and_saveexec_b64 s[6:7], vcc
	v_add_u32_e32 v40, s11, v42
	v_ashrrev_i32_e32 v41, 31, v40
	v_lshlrev_b64 v[40:41], 11, v[40:41]
	v_lshl_add_u64 v[40:41], s[62:63], 0, v[40:41]
	v_lshl_add_u64 v[40:41], v[40:41], 0, v[0:1]
	global_load_dwordx4 v[24:27], v[40:41], off
	s_mov_b64 exec, s[4:5]
	v_add_u32_e32 v42, 20, v44
	v_mov_b32_e32 v28, 0
	v_mov_b32_e32 v29, 0
	v_mov_b32_e32 v30, 0
	v_mov_b32_e32 v31, 0
	v_cmp_lt_i32_e32 vcc, s10, v42
	s_and_saveexec_b64 s[6:7], vcc
	v_add_u32_e32 v40, s11, v42
	v_ashrrev_i32_e32 v41, 31, v40
	v_lshlrev_b64 v[40:41], 11, v[40:41]
	v_lshl_add_u64 v[40:41], s[62:63], 0, v[40:41]
	v_lshl_add_u64 v[40:41], v[40:41], 0, v[0:1]
	global_load_dwordx4 v[28:31], v[40:41], off
	s_mov_b64 exec, s[4:5]
	v_add_u32_e32 v42, 24, v44
	v_mov_b32_e32 v32, 0
	v_mov_b32_e32 v33, 0
	v_mov_b32_e32 v34, 0
	v_mov_b32_e32 v35, 0
	v_cmp_lt_i32_e32 vcc, s10, v42
	s_and_saveexec_b64 s[6:7], vcc
	v_add_u32_e32 v40, s11, v42
	v_ashrrev_i32_e32 v41, 31, v40
	v_lshlrev_b64 v[40:41], 11, v[40:41]
	v_lshl_add_u64 v[40:41], s[62:63], 0, v[40:41]
	v_lshl_add_u64 v[40:41], v[40:41], 0, v[0:1]
	global_load_dwordx4 v[32:35], v[40:41], off
	s_mov_b64 exec, s[4:5]
	v_add_u32_e32 v42, 28, v44
	v_mov_b32_e32 v36, 0
	v_mov_b32_e32 v37, 0
	v_mov_b32_e32 v38, 0
	v_mov_b32_e32 v39, 0
	v_cmp_lt_i32_e32 vcc, s10, v42
	s_and_saveexec_b64 s[6:7], vcc
	v_add_u32_e32 v40, s11, v42
	v_ashrrev_i32_e32 v41, 31, v40
	v_lshlrev_b64 v[40:41], 11, v[40:41]
	v_lshl_add_u64 v[40:41], s[62:63], 0, v[40:41]
	v_lshl_add_u64 v[40:41], v[40:41], 0, v[0:1]
	global_load_dwordx4 v[36:39], v[40:41], off
	s_mov_b64 exec, s[4:5]
	s_waitcnt vmcnt(0)
	v_add_u32_e32 v42, 0, v44
	v_lshl_add_u32 v43, v42, 11, v0
	ds_write_b128 v43, v[8:11]
	v_add_u32_e32 v42, 4, v44
	v_lshl_add_u32 v43, v42, 11, v0
	ds_write_b128 v43, v[12:15]
	v_add_u32_e32 v42, 8, v44
	v_lshl_add_u32 v43, v42, 11, v0
	ds_write_b128 v43, v[16:19]
	v_add_u32_e32 v42, 12, v44
	v_lshl_add_u32 v43, v42, 11, v0
	ds_write_b128 v43, v[20:23]
	v_add_u32_e32 v42, 16, v44
	v_lshl_add_u32 v43, v42, 11, v0
	ds_write_b128 v43, v[24:27]
	v_add_u32_e32 v42, 20, v44
	v_lshl_add_u32 v43, v42, 11, v0
	ds_write_b128 v43, v[28:31]
	v_add_u32_e32 v42, 24, v44
	v_lshl_add_u32 v43, v42, 11, v0
	ds_write_b128 v43, v[32:35]
	v_add_u32_e32 v42, 28, v44
	v_lshl_add_u32 v43, v42, 11, v0
	ds_write_b128 v43, v[36:39]
	v_add_u32_e32 v42, 32, v44
	v_mov_b32_e32 v8, 0
	v_mov_b32_e32 v9, 0
	v_mov_b32_e32 v10, 0
	v_mov_b32_e32 v11, 0
	v_cmp_lt_i32_e32 vcc, s10, v42
	s_and_saveexec_b64 s[6:7], vcc
	v_add_u32_e32 v40, s11, v42
	v_ashrrev_i32_e32 v41, 31, v40
	v_lshlrev_b64 v[40:41], 11, v[40:41]
	v_lshl_add_u64 v[40:41], s[62:63], 0, v[40:41]
	v_lshl_add_u64 v[40:41], v[40:41], 0, v[0:1]
	global_load_dwordx4 v[8:11], v[40:41], off
	s_mov_b64 exec, s[4:5]
	v_add_u32_e32 v42, 36, v44
	v_mov_b32_e32 v12, 0
	v_mov_b32_e32 v13, 0
	v_mov_b32_e32 v14, 0
	v_mov_b32_e32 v15, 0
	v_cmp_lt_i32_e32 vcc, s10, v42
	s_and_saveexec_b64 s[6:7], vcc
	v_add_u32_e32 v40, s11, v42
	v_ashrrev_i32_e32 v41, 31, v40
	v_lshlrev_b64 v[40:41], 11, v[40:41]
	v_lshl_add_u64 v[40:41], s[62:63], 0, v[40:41]
	v_lshl_add_u64 v[40:41], v[40:41], 0, v[0:1]
	global_load_dwordx4 v[12:15], v[40:41], off
	s_mov_b64 exec, s[4:5]
	v_add_u32_e32 v42, 40, v44
	v_mov_b32_e32 v16, 0
	v_mov_b32_e32 v17, 0
	v_mov_b32_e32 v18, 0
	v_mov_b32_e32 v19, 0
	v_cmp_lt_i32_e32 vcc, s10, v42
	s_and_saveexec_b64 s[6:7], vcc
	v_add_u32_e32 v40, s11, v42
	v_ashrrev_i32_e32 v41, 31, v40
	v_lshlrev_b64 v[40:41], 11, v[40:41]
	v_lshl_add_u64 v[40:41], s[62:63], 0, v[40:41]
	v_lshl_add_u64 v[40:41], v[40:41], 0, v[0:1]
	global_load_dwordx4 v[16:19], v[40:41], off
	s_mov_b64 exec, s[4:5]
	v_add_u32_e32 v42, 44, v44
	v_mov_b32_e32 v20, 0
	v_mov_b32_e32 v21, 0
	v_mov_b32_e32 v22, 0
	v_mov_b32_e32 v23, 0
	v_cmp_lt_i32_e32 vcc, s10, v42
	s_and_saveexec_b64 s[6:7], vcc
	v_add_u32_e32 v40, s11, v42
	v_ashrrev_i32_e32 v41, 31, v40
	v_lshlrev_b64 v[40:41], 11, v[40:41]
	v_lshl_add_u64 v[40:41], s[62:63], 0, v[40:41]
	v_lshl_add_u64 v[40:41], v[40:41], 0, v[0:1]
	global_load_dwordx4 v[20:23], v[40:41], off
	s_mov_b64 exec, s[4:5]
	v_add_u32_e32 v42, 48, v44
	v_mov_b32_e32 v24, 0
	v_mov_b32_e32 v25, 0
	v_mov_b32_e32 v26, 0
	v_mov_b32_e32 v27, 0
	v_cmp_lt_i32_e32 vcc, s10, v42
	s_and_saveexec_b64 s[6:7], vcc
	v_add_u32_e32 v40, s11, v42
	v_ashrrev_i32_e32 v41, 31, v40
	v_lshlrev_b64 v[40:41], 11, v[40:41]
	v_lshl_add_u64 v[40:41], s[62:63], 0, v[40:41]
	v_lshl_add_u64 v[40:41], v[40:41], 0, v[0:1]
	global_load_dwordx4 v[24:27], v[40:41], off
	s_mov_b64 exec, s[4:5]
	v_add_u32_e32 v42, 52, v44
	v_mov_b32_e32 v28, 0
	v_mov_b32_e32 v29, 0
	v_mov_b32_e32 v30, 0
	v_mov_b32_e32 v31, 0
	v_cmp_lt_i32_e32 vcc, s10, v42
	s_and_saveexec_b64 s[6:7], vcc
	v_add_u32_e32 v40, s11, v42
	v_ashrrev_i32_e32 v41, 31, v40
	v_lshlrev_b64 v[40:41], 11, v[40:41]
	v_lshl_add_u64 v[40:41], s[62:63], 0, v[40:41]
	v_lshl_add_u64 v[40:41], v[40:41], 0, v[0:1]
	global_load_dwordx4 v[28:31], v[40:41], off
	s_mov_b64 exec, s[4:5]
	v_add_u32_e32 v42, 56, v44
	v_mov_b32_e32 v32, 0
	v_mov_b32_e32 v33, 0
	v_mov_b32_e32 v34, 0
	v_mov_b32_e32 v35, 0
	v_cmp_lt_i32_e32 vcc, s10, v42
	s_and_saveexec_b64 s[6:7], vcc
	v_add_u32_e32 v40, s11, v42
	v_ashrrev_i32_e32 v41, 31, v40
	v_lshlrev_b64 v[40:41], 11, v[40:41]
	v_lshl_add_u64 v[40:41], s[62:63], 0, v[40:41]
	v_lshl_add_u64 v[40:41], v[40:41], 0, v[0:1]
	global_load_dwordx4 v[32:35], v[40:41], off
	s_mov_b64 exec, s[4:5]
	v_add_u32_e32 v42, 60, v44
	v_mov_b32_e32 v36, 0
	v_mov_b32_e32 v37, 0
	v_mov_b32_e32 v38, 0
	v_mov_b32_e32 v39, 0
	v_cmp_lt_i32_e32 vcc, s10, v42
	s_nop 1
	s_and_b64 vcc, vcc, s[12:13]
	s_and_saveexec_b64 s[6:7], vcc
	v_add_u32_e32 v40, s11, v42
	v_ashrrev_i32_e32 v41, 31, v40
	v_lshlrev_b64 v[40:41], 11, v[40:41]
	v_lshl_add_u64 v[40:41], s[62:63], 0, v[40:41]
	v_lshl_add_u64 v[40:41], v[40:41], 0, v[0:1]
	global_load_dwordx4 v[36:39], v[40:41], off
	s_mov_b64 exec, s[4:5]
	s_waitcnt vmcnt(0)
	v_add_u32_e32 v42, 32, v44
	v_lshl_add_u32 v43, v42, 11, v0
	ds_write_b128 v43, v[8:11]
	v_add_u32_e32 v42, 36, v44
	v_lshl_add_u32 v43, v42, 11, v0
	ds_write_b128 v43, v[12:15]
	v_add_u32_e32 v42, 40, v44
	v_lshl_add_u32 v43, v42, 11, v0
	ds_write_b128 v43, v[16:19]
	v_add_u32_e32 v42, 44, v44
	v_lshl_add_u32 v43, v42, 11, v0
	ds_write_b128 v43, v[20:23]
	v_add_u32_e32 v42, 48, v44
	v_lshl_add_u32 v43, v42, 11, v0
	ds_write_b128 v43, v[24:27]
	v_add_u32_e32 v42, 52, v44
	v_lshl_add_u32 v43, v42, 11, v0
	ds_write_b128 v43, v[28:31]
	v_add_u32_e32 v42, 56, v44
	v_lshl_add_u32 v43, v42, 11, v0
	ds_write_b128 v43, v[32:35]
	s_and_b64 exec, s[4:5], s[12:13]
	v_add_u32_e32 v42, 60, v44
	v_lshl_add_u32 v43, v42, 11, v0
	ds_write_b128 v43, v[36:39]
	s_mov_b64 exec, s[4:5]
